# residual-add epilogues (P10, P15): first row-group's full vmcnt(0) drain replaced by the counted waits the later row-groups use
# speedup vs baseline: 1.0031x; 1.0031x over previous
.LBB0_879:
	s_or_b64 exec, exec, s[38:39]
	s_waitcnt lgkmcnt(0)
	v_lshlrev_b64 v[128:129], 10, v[184:185]
	s_waitcnt vmcnt(5)
	v_lshlrev_b32_e32 v130, 16, v140
	v_and_b32_e32 v131, 0xffff0000, v140
	v_lshlrev_b32_e32 v132, 16, v141
	v_and_b32_e32 v133, 0xffff0000, v141
	v_lshlrev_b32_e32 v134, 16, v142
	v_and_b32_e32 v135, 0xffff0000, v142
	v_lshlrev_b32_e32 v140, 16, v143
	v_and_b32_e32 v141, 0xffff0000, v143
	v_lshl_add_u64 v[142:143], v[128:129], 0, v[172:173]
	v_or_b32_e32 v128, 32, v182
	v_ashrrev_i32_e32 v129, 31, v128
	v_pk_fma_f32 v[124:125], v[124:125], v[68:69], v[130:131]
	v_pk_fma_f32 v[126:127], v[126:127], v[70:71], v[132:133]
	v_pk_fma_f32 v[120:121], v[120:121], v[76:77], v[134:135]
	v_pk_fma_f32 v[122:123], v[122:123], v[78:79], v[140:141]
	v_lshlrev_b64 v[200:201], 11, v[128:129]
	v_pk_add_f32 v[130:131], v[126:127], 0 op_sel_hi:[1,0]
	v_pk_add_f32 v[132:133], v[124:125], 0 op_sel_hi:[1,0]
	v_pk_add_f32 v[134:135], v[122:123], 0 op_sel_hi:[1,0]
	v_pk_add_f32 v[140:141], v[120:121], 0 op_sel_hi:[1,0]
	v_lshlrev_b64 v[142:143], 1, v[142:143]
	v_lshl_add_u64 v[200:201], v[180:181], 0, v[200:201]
	v_cvt_pk_bf16_f32 v120, v132, v133
	v_cvt_pk_bf16_f32 v121, v130, v131
	v_cvt_pk_bf16_f32 v122, v140, v141
	v_cvt_pk_bf16_f32 v123, v134, v135
	v_lshl_add_u64 v[202:203], s[30:31], 0, v[142:143]
	v_readlane_b32 s38, v243, 54
	global_load_dwordx4 v[124:127], v[200:201], off
	v_pk_mul_f32 v[204:205], v[164:165], v[134:135]
	global_store_dwordx4 v[202:203], v[120:123], off
	v_pk_mul_f32 v[206:207], v[166:167], v[140:141]
	v_readlane_b32 s39, v243, 55
	v_pk_mul_f32 v[122:123], v[160:161], v[130:131]
	v_pk_mul_f32 v[120:121], v[162:163], v[132:133]
	v_mul_f32_e32 v133, v133, v133
	v_cvt_pk_bf16_f32 v120, v120, v121
	v_cvt_pk_bf16_f32 v121, v122, v123
	v_cvt_pk_bf16_f32 v122, v206, v207
	v_cvt_pk_bf16_f32 v123, v204, v205
	v_lshl_add_u64 v[204:205], s[38:39], 0, v[142:143]
	global_store_dwordx4 v[204:205], v[120:123], off
	global_load_dwordx4 v[120:123], v[200:201], off offset:256
	v_mul_f32_e32 v131, v131, v131
	v_fmac_f32_e32 v133, v132, v132
	v_fmac_f32_e32 v131, v130, v130
	v_add_f32_e32 v130, v133, v131
	v_mul_f32_e32 v131, v141, v141
	v_mul_f32_e32 v132, v135, v135
	s_waitcnt vmcnt(6)
	v_lshlrev_b32_e32 v200, 16, v136
	v_and_b32_e32 v201, 0xffff0000, v136
	v_lshlrev_b32_e32 v136, 16, v137
	v_and_b32_e32 v137, 0xffff0000, v137
	v_lshlrev_b32_e32 v204, 16, v138
	v_and_b32_e32 v205, 0xffff0000, v138
	v_lshlrev_b32_e32 v138, 16, v139
	v_and_b32_e32 v139, 0xffff0000, v139
	v_fmac_f32_e32 v131, v140, v140
	v_fmac_f32_e32 v132, v134, v134
	v_add_f32_e32 v131, v131, v132
	v_pk_fma_f32 v[116:117], v[116:117], v[88:89], v[200:201]
	v_pk_fma_f32 v[118:119], v[118:119], v[90:91], v[136:137]
	v_pk_fma_f32 v[112:113], v[112:113], v[92:93], v[204:205]
	v_pk_fma_f32 v[114:115], v[114:115], v[94:95], v[138:139]
	v_add_f32_e32 v134, v130, v131
	v_pk_add_f32 v[118:119], v[118:119], 0 op_sel_hi:[1,0]
	v_pk_add_f32 v[116:117], v[116:117], 0 op_sel_hi:[1,0]
	v_pk_add_f32 v[130:131], v[114:115], 0 op_sel_hi:[1,0]
	v_pk_add_f32 v[132:133], v[112:113], 0 op_sel_hi:[1,0]
	v_cvt_pk_bf16_f32 v112, v116, v117
	v_cvt_pk_bf16_f32 v113, v118, v119
	v_cvt_pk_bf16_f32 v114, v132, v133
	v_cvt_pk_bf16_f32 v115, v130, v131
	global_store_dwordx4 v[202:203], v[112:115], off offset:256
	v_or_b32_e32 v142, 0x100, v142
	s_nop 0
	v_mul_f32_e32 v112, v117, v117
	v_mul_f32_e32 v113, v119, v119
	v_fmac_f32_e32 v112, v116, v116
	v_fmac_f32_e32 v113, v118, v118
	v_add_f32_e32 v112, v112, v113
	v_mul_f32_e32 v113, v133, v133
	v_mul_f32_e32 v114, v131, v131
	v_fmac_f32_e32 v113, v132, v132
	v_fmac_f32_e32 v114, v130, v130
	v_add_f32_e32 v112, v134, v112
	v_add_f32_e32 v113, v113, v114
	v_add_f32_e32 v134, v113, v112
	v_pk_mul_f32 v[112:113], v[174:175], v[118:119]
	v_pk_mul_f32 v[118:119], v[178:179], v[130:131]
	v_mov_b32_e32 v244, v134
	v_mov_b32_e32 v245, v134
	s_nop 1
	v_permlane16_swap_b32_e32 v244, v245
	v_pk_mul_f32 v[114:115], v[176:177], v[116:117]
	v_pk_mul_f32 v[116:117], v[170:171], v[132:133]
	v_cvt_pk_bf16_f32 v114, v114, v115
	v_cvt_pk_bf16_f32 v115, v112, v113
	s_waitcnt lgkmcnt(0)
	v_add_f32_e32 v112, v244, v245
	v_mov_b32_e32 v246, v112
	v_mov_b32_e32 v247, v112
	s_nop 1
	v_permlane32_swap_b32_e32 v246, v247
	v_cvt_pk_bf16_f32 v116, v116, v117
	v_cvt_pk_bf16_f32 v117, v118, v119
	v_lshl_add_u64 v[118:119], s[38:39], 0, v[142:143]
	global_store_dwordx4 v[118:119], v[114:117], off
	s_and_saveexec_b64 s[38:39], s[4:5]
	s_cbranch_execz .LBB0_881
	v_lshlrev_b64 v[114:115], 6, v[184:185]
	v_lshl_add_u64 v[114:115], s[16:17], 0, v[114:115]
	v_lshl_add_u64 v[114:115], s[0:1], 2, v[114:115]
	s_lshl_b32 s40, s58, 2
	s_mov_b32 s41, s3
	v_lshl_add_u64 v[114:115], v[114:115], 0, s[40:41]
	s_waitcnt lgkmcnt(0)
	v_add_f32_e32 v112, v246, v247
	global_store_dword v[114:115], v112, off

.LBB0_1301:
	s_or_b64 exec, exec, s[42:43]
	s_waitcnt lgkmcnt(0)
	v_lshlrev_b64 v[128:129], 10, v[166:167]
	s_waitcnt vmcnt(5)
	v_lshlrev_b32_e32 v130, 16, v140
	v_and_b32_e32 v131, 0xffff0000, v140
	v_lshlrev_b32_e32 v132, 16, v141
	v_and_b32_e32 v133, 0xffff0000, v141
	v_lshlrev_b32_e32 v134, 16, v142
	v_and_b32_e32 v135, 0xffff0000, v142
	v_lshlrev_b32_e32 v140, 16, v143
	v_and_b32_e32 v141, 0xffff0000, v143
	v_lshl_add_u64 v[142:143], v[128:129], 0, v[156:157]
	v_or_b32_e32 v128, 32, v164
	v_ashrrev_i32_e32 v129, 31, v128
	v_pk_fma_f32 v[124:125], v[124:125], v[64:65], v[130:131]
	v_pk_fma_f32 v[126:127], v[126:127], v[66:67], v[132:133]
	v_pk_fma_f32 v[120:121], v[120:121], v[80:81], v[134:135]
	v_pk_fma_f32 v[122:123], v[122:123], v[82:83], v[140:141]
	v_lshlrev_b64 v[214:215], 11, v[128:129]
	v_pk_add_f32 v[130:131], v[188:189], v[126:127]
	v_pk_add_f32 v[132:133], v[186:187], v[124:125]
	v_pk_add_f32 v[134:135], v[198:199], v[122:123]
	v_pk_add_f32 v[140:141], v[190:191], v[120:121]
	v_lshlrev_b64 v[142:143], 1, v[142:143]
	v_lshl_add_u64 v[214:215], v[158:159], 0, v[214:215]
	v_cvt_pk_bf16_f32 v120, v132, v133
	v_cvt_pk_bf16_f32 v121, v130, v131
	v_cvt_pk_bf16_f32 v122, v140, v141
	v_cvt_pk_bf16_f32 v123, v134, v135
	v_lshl_add_u64 v[216:217], s[0:1], 0, v[142:143]
	global_load_dwordx4 v[124:127], v[214:215], off
	v_pk_mul_f32 v[218:219], v[162:163], v[134:135]
	global_store_dwordx4 v[216:217], v[120:123], off
	v_pk_mul_f32 v[220:221], v[160:161], v[140:141]
	s_nop 0
	v_pk_mul_f32 v[122:123], v[154:155], v[130:131]
	v_pk_mul_f32 v[120:121], v[152:153], v[132:133]
	v_mul_f32_e32 v133, v133, v133
	v_cvt_pk_bf16_f32 v120, v120, v121
	v_cvt_pk_bf16_f32 v121, v122, v123
	v_cvt_pk_bf16_f32 v122, v220, v221
	v_cvt_pk_bf16_f32 v123, v218, v219
	v_lshl_add_u64 v[218:219], s[6:7], 0, v[142:143]
	global_store_dwordx4 v[218:219], v[120:123], off
	global_load_dwordx4 v[120:123], v[214:215], off offset:256
	v_mul_f32_e32 v131, v131, v131
	v_fmac_f32_e32 v133, v132, v132
	v_fmac_f32_e32 v131, v130, v130
	v_add_f32_e32 v130, v133, v131
	v_mul_f32_e32 v131, v141, v141
	v_mul_f32_e32 v132, v135, v135
	s_waitcnt vmcnt(6)
	v_lshlrev_b32_e32 v214, 16, v136
	v_and_b32_e32 v215, 0xffff0000, v136
	v_lshlrev_b32_e32 v136, 16, v137
	v_and_b32_e32 v137, 0xffff0000, v137
	v_lshlrev_b32_e32 v218, 16, v138
	v_and_b32_e32 v219, 0xffff0000, v138
	v_lshlrev_b32_e32 v138, 16, v139
	v_and_b32_e32 v139, 0xffff0000, v139
	v_fmac_f32_e32 v131, v140, v140
	v_fmac_f32_e32 v132, v134, v134
	v_add_f32_e32 v131, v131, v132
	v_pk_fma_f32 v[116:117], v[116:117], v[76:77], v[214:215]
	v_pk_fma_f32 v[118:119], v[118:119], v[78:79], v[136:137]
	v_pk_fma_f32 v[112:113], v[112:113], v[84:85], v[218:219]
	v_pk_fma_f32 v[114:115], v[114:115], v[86:87], v[138:139]
	v_add_f32_e32 v134, v130, v131
	v_pk_add_f32 v[118:119], v[192:193], v[118:119]
	v_pk_add_f32 v[116:117], v[194:195], v[116:117]
	v_pk_add_f32 v[130:131], v[200:201], v[114:115]
	v_pk_add_f32 v[132:133], v[196:197], v[112:113]
	v_cvt_pk_bf16_f32 v112, v116, v117
	v_cvt_pk_bf16_f32 v113, v118, v119
	v_cvt_pk_bf16_f32 v114, v132, v133
	v_cvt_pk_bf16_f32 v115, v130, v131
	global_store_dwordx4 v[216:217], v[112:115], off offset:256
	v_or_b32_e32 v142, 0x100, v142
	s_nop 0
	v_mul_f32_e32 v112, v117, v117
	v_mul_f32_e32 v113, v119, v119
	v_fmac_f32_e32 v112, v116, v116
	v_fmac_f32_e32 v113, v118, v118
	v_add_f32_e32 v112, v112, v113
	v_mul_f32_e32 v113, v133, v133
	v_mul_f32_e32 v114, v131, v131
	v_fmac_f32_e32 v113, v132, v132
	v_fmac_f32_e32 v114, v130, v130
	v_add_f32_e32 v112, v134, v112
	v_add_f32_e32 v113, v113, v114
	v_add_f32_e32 v134, v113, v112
	v_pk_mul_f32 v[112:113], v[148:149], v[118:119]
	v_pk_mul_f32 v[118:119], v[146:147], v[130:131]
	v_mov_b32_e32 v244, v134
	v_mov_b32_e32 v245, v134
	s_nop 1
	v_permlane16_swap_b32_e32 v244, v245
	v_pk_mul_f32 v[114:115], v[150:151], v[116:117]
	v_pk_mul_f32 v[116:117], v[144:145], v[132:133]
	v_cvt_pk_bf16_f32 v114, v114, v115
	v_cvt_pk_bf16_f32 v115, v112, v113
	s_waitcnt lgkmcnt(0)
	v_add_f32_e32 v112, v244, v245
	v_mov_b32_e32 v246, v112
	v_mov_b32_e32 v247, v112
	s_nop 1
	v_permlane32_swap_b32_e32 v246, v247
	v_cvt_pk_bf16_f32 v116, v116, v117
	v_cvt_pk_bf16_f32 v117, v118, v119
	v_lshl_add_u64 v[118:119], s[6:7], 0, v[142:143]
	global_store_dwordx4 v[118:119], v[114:117], off
	s_and_saveexec_b64 s[42:43], s[2:3]
	s_cbranch_execz .LBB0_1303
	v_lshlrev_b64 v[114:115], 6, v[166:167]
	v_lshl_add_u64 v[114:115], s[10:11], 0, v[114:115]
	v_lshl_add_u64 v[114:115], s[40:41], 2, v[114:115]
	s_lshl_b32 s44, s69, 2
	s_mov_b32 s45, s13
	v_lshl_add_u64 v[114:115], v[114:115], 0, s[44:45]
	s_waitcnt lgkmcnt(0)
	v_add_f32_e32 v112, v246, v247
	global_store_dword v[114:115], v112, off
